# v37 plus one 4-byte pad so the SwiGLU, EpiStore and residual GEMM K-loop heads sit at 0 mod 8 bytes (code placement experiment)
# speedup vs baseline: 1.0035x; 1.0035x over previous
; #define LDS_BARRIER() do { asm volatile("s_waitcnt lgkmcnt(0)" ::: "memory"); __builtin_amdgcn_s_barrier(); asm volatile("" ::: "memory"); } while (0)
; #define LAUNDER_V(x) asm volatile("" : "+v"(x))
; #define LAUNDER_S(x) asm volatile("" : "+s"(x))
;     ...
;     int tid = threadIdx.x; LAUNDER_V(tid); int bid = blockIdx.x; LAUNDER_S(bid);
;     const int nkt = K / 64, ntiles = (Ntot / 128) * nkt;
;     float v[16];
;     ...
;     const int cstride = nwg ? nwg : (int)gridDim.x; bid -= wg0;
;     if (bid < 0) return;
;     if (bid < ntiles) CONVW_LOAD(bid);
;     for (int t = bid; t < ntiles; t += cstride) {
;         const int n0 = (t / nkt) * 128, k0 = (t % nkt) * 64;
; #pragma unroll
;         for (int it = 0; it < 16; ++it) { const int e = tid + 512 * it, kk = e >> 7, nn = e & 127; tile[kk * 129 + nn] = v[it]; }
;         LDS_BARRIER();
;         if (t + cstride < ntiles) CONVW_LOAD(t + cstride);
; #pragma unroll
;         for (int it = 0; it < 8; ++it) {
;             const int e = tid + 512 * it, nn = e >> 5, kp = e & 31, n = n0 + nn;
;             const int dr = (inter >= 0) ? ((n >> 7) * 256 + inter * 128 + (n & 127)) : n;
;             h16x2 o; o[0] = (h16)tile[(2 * kp) * 129 + nn]; o[1] = (h16)tile[(2 * kp + 1) * 129 + nn];
;             gst((h16x2*)(dst + (unsigned)dr * K + k0 + 2 * kp), o);
.Lh2_skip:
	s_nop 0
	v_readlane_b32 s8, v253, 34
	s_lshl_b32 s0, s3, 2
	v_readlane_b32 s22, v253, 48
	v_readlane_b32 s10, v253, 36
	v_readlane_b32 s23, v253, 49
	s_add_u32 s0, s22, s0
	s_addc_u32 s1, s23, 0
	s_add_i32 s10, s4, 0xffffff80
	s_lshl_b32 s5, s10, 3
	s_and_b32 s5, s5, 0x380
	v_and_b32_e32 v20, 0x7f, v18
	s_lshl_b32 s4, s4, 6
	v_or_b32_e32 v0, s5, v20
	s_and_b32 s4, s4, 0x3c0
	v_lshlrev_b32_e32 v32, 2, v0
	v_ashrrev_i32_e32 v19, 7, v18
	v_add_u32_e32 v23, 0x200, v18
	v_lshl_add_u64 v[16:17], s[0:1], 0, v[32:33]
	v_add_lshl_u32 v32, s4, v19, 10
	v_ashrrev_i32_e32 v53, 7, v23
	v_add_u32_e32 v25, 0x400, v18
	v_lshl_add_u64 v[0:1], v[32:33], 2, v[16:17]
	v_add_lshl_u32 v32, s4, v53, 10
	v_ashrrev_i32_e32 v52, 7, v25
	v_add_u32_e32 v27, 0x600, v18
	v_lshl_add_u64 v[2:3], v[32:33], 2, v[16:17]
	v_add_lshl_u32 v32, s4, v52, 10
	v_ashrrev_i32_e32 v51, 7, v27
	v_add_u32_e32 v29, 0x800, v18
	global_load_dword v0, v[0:1], off
	v_ashrrev_i32_e32 v50, 7, v29
	global_load_dword v1, v[2:3], off
	v_lshl_add_u64 v[2:3], v[32:33], 2, v[16:17]
	v_add_lshl_u32 v32, s4, v51, 10
	v_add_u32_e32 v31, 0xa00, v18
	v_lshl_add_u64 v[4:5], v[32:33], 2, v[16:17]
	v_add_lshl_u32 v32, s4, v50, 10
	v_ashrrev_i32_e32 v49, 7, v31
	v_add_u32_e32 v35, 0xc00, v18
	global_load_dword v2, v[2:3], off
	v_ashrrev_i32_e32 v48, 7, v35
	global_load_dword v3, v[4:5], off
	v_lshl_add_u64 v[4:5], v[32:33], 2, v[16:17]
	v_add_lshl_u32 v32, s4, v49, 10
	v_add_u32_e32 v37, 0xe00, v18
	v_lshl_add_u64 v[6:7], v[32:33], 2, v[16:17]
	v_add_lshl_u32 v32, s4, v48, 10
	v_ashrrev_i32_e32 v47, 7, v37
	global_load_dword v4, v[4:5], off
	v_readlane_b32 s9, v253, 35
	global_load_dword v5, v[6:7], off
	v_lshl_add_u64 v[6:7], v[32:33], 2, v[16:17]
	v_add_lshl_u32 v32, s4, v47, 10
	v_lshl_add_u64 v[8:9], v[32:33], 2, v[16:17]
	global_load_dword v6, v[6:7], off
	v_lshl_add_u32 v70, v20, 2, 0
	global_load_dword v7, v[8:9], off
	v_add_u32_e32 v8, 0x1000, v18
	v_ashrrev_i32_e32 v46, 7, v8
	v_add_lshl_u32 v32, s4, v46, 10
	v_lshl_add_u64 v[8:9], v[32:33], 2, v[16:17]
	global_load_dword v8, v[8:9], off
	v_add_u32_e32 v9, 0x1200, v18
	v_ashrrev_i32_e32 v45, 7, v9
	v_add_lshl_u32 v32, s4, v45, 10
	v_lshl_add_u64 v[10:11], v[32:33], 2, v[16:17]
	global_load_dword v9, v[10:11], off
	v_add_u32_e32 v10, 0x1400, v18
	v_ashrrev_i32_e32 v44, 7, v10
	v_add_lshl_u32 v32, s4, v44, 10
	v_lshl_add_u64 v[10:11], v[32:33], 2, v[16:17]
	global_load_dword v10, v[10:11], off
	v_add_u32_e32 v11, 0x1600, v18
	v_ashrrev_i32_e32 v43, 7, v11
	v_add_lshl_u32 v32, s4, v43, 10
	v_lshl_add_u64 v[12:13], v[32:33], 2, v[16:17]
	global_load_dword v11, v[12:13], off
	v_add_u32_e32 v12, 0x1800, v18
	v_ashrrev_i32_e32 v42, 7, v12
	v_add_lshl_u32 v32, s4, v42, 10
	v_lshl_add_u64 v[12:13], v[32:33], 2, v[16:17]
	global_load_dword v12, v[12:13], off
	v_add_u32_e32 v13, 0x1a00, v18
	v_ashrrev_i32_e32 v41, 7, v13
	v_add_lshl_u32 v32, s4, v41, 10
	v_lshl_add_u64 v[14:15], v[32:33], 2, v[16:17]
	global_load_dword v13, v[14:15], off
	v_add_u32_e32 v14, 0x1c00, v18
	v_ashrrev_i32_e32 v40, 7, v14
	v_add_lshl_u32 v32, s4, v40, 10
	v_lshl_add_u64 v[14:15], v[32:33], 2, v[16:17]
	global_load_dword v14, v[14:15], off
	v_add_u32_e32 v15, 0x1e00, v18
	v_ashrrev_i32_e32 v39, 7, v15
	v_add_lshl_u32 v32, s4, v39, 10
	v_lshl_add_u64 v[16:17], v[32:33], 2, v[16:17]
	global_load_dword v15, v[16:17], off
	v_lshlrev_b32_e32 v16, 1, v18
	v_and_b32_e32 v16, 62, v16
	v_readlane_b32 s4, v255, 7
	v_lshlrev_b32_e32 v32, 1, v16
	v_readlane_b32 s5, v255, 8
	v_mad_u32_u24 v38, v16, s82, 0
	v_ashrrev_i32_e32 v21, 5, v18
	v_lshl_add_u64 v[16:17], s[4:5], 0, v[32:33]
	v_readlane_b32 s5, v253, 56
	v_mul_lo_u32 v18, v19, s82
	v_mul_lo_u32 v32, v53, s82
	v_mul_lo_u32 v57, v52, s82
	v_mul_lo_u32 v58, v51, s82
	v_mul_lo_u32 v59, v50, s82
	v_mul_lo_u32 v60, v49, s82
	v_mul_lo_u32 v61, v48, s82
	v_mul_lo_u32 v62, v47, s82
	v_mul_lo_u32 v63, v46, s82
	v_mul_lo_u32 v64, v45, s82
	v_mul_lo_u32 v65, v44, s82
	v_mul_lo_u32 v66, v43, s82
	v_mul_lo_u32 v67, v42, s82
	v_mul_lo_u32 v68, v41, s82
	v_mul_lo_u32 v69, v40, s82
	v_mul_lo_u32 v71, v39, s82
	v_ashrrev_i32_e32 v23, 5, v23
	v_ashrrev_i32_e32 v25, 5, v25
	v_ashrrev_i32_e32 v27, 5, v27
	v_ashrrev_i32_e32 v29, 5, v29
	v_ashrrev_i32_e32 v31, 5, v31
	v_ashrrev_i32_e32 v35, 5, v35
	v_ashrrev_i32_e32 v37, 5, v37
	s_add_i32 s4, s5, s10
	v_lshl_add_u32 v22, v21, 2, v38
	v_lshl_add_u32 v24, v23, 2, v38
	v_lshl_add_u32 v26, v25, 2, v38
	v_lshl_add_u32 v28, v27, 2, v38
	v_lshl_add_u32 v30, v29, 2, v38
	v_lshl_add_u32 v34, v31, 2, v38
	v_lshl_add_u32 v36, v35, 2, v38
	v_lshl_add_u32 v38, v37, 2, v38
	s_lshl_b32 s6, s10, 6
	s_lshl_b32 s7, s5, 6
	v_lshlrev_b32_e32 v39, 10, v39
	s_lshl_b32 s8, s4, 16
	s_lshl_b32 s9, s5, 16
	v_lshlrev_b32_e32 v40, 10, v40
	v_lshlrev_b32_e32 v41, 10, v41
	v_lshlrev_b32_e32 v42, 10, v42
	v_lshlrev_b32_e32 v43, 10, v43
	v_lshlrev_b32_e32 v44, 10, v44
	v_lshlrev_b32_e32 v45, 10, v45
	v_lshlrev_b32_e32 v46, 10, v46
	v_lshlrev_b32_e32 v47, 10, v47
	v_lshlrev_b32_e32 v48, 10, v48
	v_lshlrev_b32_e32 v49, 10, v49
	v_lshlrev_b32_e32 v50, 10, v50
	v_lshlrev_b32_e32 v51, 10, v51
	v_lshlrev_b32_e32 v52, 10, v52
	v_lshlrev_b32_e32 v53, 10, v53
	v_lshlrev_b32_e32 v54, 10, v19
	v_add_u32_e32 v55, v70, v18
	v_add_u32_e32 v56, v70, v32
	v_add_u32_e32 v57, v70, v57
	v_add_u32_e32 v58, v70, v58
	v_add_u32_e32 v59, v70, v59
	v_add_u32_e32 v60, v70, v60
	v_add_u32_e32 v61, v70, v61
	v_add_u32_e32 v62, v70, v62
	v_add_u32_e32 v63, v70, v63
	v_add_u32_e32 v64, v70, v64
	v_add_u32_e32 v65, v70, v65
	v_add_u32_e32 v66, v70, v66
	v_add_u32_e32 v67, v70, v67
	v_add_u32_e32 v68, v70, v68
	v_add_u32_e32 v69, v70, v69
	v_add_u32_e32 v70, v70, v71
	v_readlane_b32 s11, v253, 37
	v_readlane_b32 s12, v253, 38
	v_readlane_b32 s13, v253, 39
	v_readlane_b32 s14, v253, 40
	v_readlane_b32 s15, v253, 41
	v_readlane_b32 s16, v253, 42
	v_readlane_b32 s17, v253, 43
	v_readlane_b32 s18, v253, 44
	v_readlane_b32 s19, v253, 45
	v_readlane_b32 s20, v253, 46
	v_readlane_b32 s21, v253, 47
	s_branch .LBB0_230
